# scan: state update as B^T (x*w) instead of (B*w)^T x, raw x tile read directly for the Y product (no selects)
# speedup vs baseline: 1.0523x; 1.0038x over previous
; __device__ __forceinline__ int opaque_tid() { int t = threadIdx.x; asm volatile("" : "+v"(t)); return t; }
; template <bool DRY>
; __device__ __forceinline__ void ssd_chunk(SsdRegs& R, f32x4 (&st)[2], LAS unsigned char* L, bf16_t* BIG, const float* DT, float* SSQY, const SsdItem& I, int c, int tid, int lane, int wave, int li, int pi, int c16, int q4) {
;     ...
;     const int XI = XI0 + (c & 1) * 6144, SB = SB0 + (c & 1) * 8704;
;     const int trB = (8 * q4 + (c16 >> 2)) * PB + (c16 & 3) * 8, trX = (8 * q4 + (c16 >> 2)) * PX + (c16 & 3) * 8;
; template <bool DRY>
; __device__ __forceinline__ void phase_ssd_scan(const Args& a, int j, unsigned char* lds_raw) {
;     ...
;     const int tid = opaque_tid(), lane = tid & 63, wave = __builtin_amdgcn_readfirstlane(tid >> 6);
;     const int role = (wave == 1) ? 6 : ((wave == 6) ? 1 : wave);
;     const int c16 = lane & 15, q4 = lane >> 4, li = role >> 1, pi = role & 1;
;     for (int it = blockIdx.x; it < 256; it += gridDim.x) {
;         const int xc = it & 7, slot = it >> 3, pair = xc + 8 * (slot >> 3), sub = slot & 7;
;         SsdItem I; I.b = pair >> 3; I.g = pair & 7; I.h = I.g * 4 + (sub >> 1); I.ph = sub & 1;
;         I.Ah = -__expf(A_log[I.h]); I.Dh = Dp[I.h];
; #pragma unroll
;         for (int i = 0; i < 2; ++i) { I.offB[i] = (unsigned)(lane * BIGW + 4096 + I.g * 128 + (wave + 8 * i) * 8) * 2u; const int id = tid + 512 * i; I.offC[i] = (unsigned)((id >> 4) * BIGW + 5120 + I.g * 128 + (id & 15) * 8) * 2u; }
;         I.offX = (unsigned)(lane * BIGW + DI_ + I.h * 64 + I.ph * 32 + wave * 8) * 2u;
;         I.offZ = (unsigned)((16 * li + c16) * BIGW + I.h * 64 + I.ph * 32 + 16 * pi + 4 * q4) * 2u;
;         I.offDT = (unsigned)(lane * 32 + I.h) * 4u;
;         f32x4 st[2]; st[0] = (f32x4){0.f, 0.f, 0.f, 0.f}; st[1] = (f32x4){0.f, 0.f, 0.f, 0.f};
;         SsdRegs R0, R1; R0.rx = make_uint4(0, 0, 0, 0); R1.rx = make_uint4(0, 0, 0, 0);
;         ssd_load(R0, BIG, DT, I, 0, wave);
;         ssd_load(R1, BIG, DT, I, 1, wave);
.LBB0_705:
	s_cmp_lt_i32 s74, 2
	s_mov_b64 s[0:1], -1
	s_cbranch_scc1 .LBB0_752
	s_cmp_eq_u32 s74, 2
	s_cbranch_scc0 .LBB0_751
	v_readlane_b32 s0, v253, 63
	s_waitcnt vmcnt(0) lgkmcnt(0)
	v_mov_b32_e32 v2, v0
	v_readlane_b32 s1, v254, 0
	s_andn2_b64 vcc, exec, s[0:1]
	v_readfirstlane_b32 s0, v2
	s_cbranch_vccnz .LBB0_751
	s_cmp_eq_u32 s27, 0x100
	s_cselect_b32 s100, 2, 7
	s_cselect_b32 s101, 8, 2
	v_writelane_b32 v255, s74, 31
	v_writelane_b32 v255, s69, 32
	s_mov_b32 s2, s22
	v_writelane_b32 v255, s2, 12
	v_and_b32_e32 v5, 63, v2
	v_mov_b32_e32 v1, 0x1000
	v_writelane_b32 v255, s3, 13
	s_lshl_b32 s2, s22, 5
	s_ashr_i32 s3, s2, 31
	s_lshl_b64 s[2:3], s[2:3], 2
	s_waitcnt lgkmcnt(0)
	s_add_u32 s4, s54, s2
	s_addc_u32 s5, s55, s3
	s_add_u32 s2, s56, s2
	s_addc_u32 s3, s57, s3
	s_ashr_i32 s0, s0, 6
	s_cmp_lg_u32 s0, 6
	v_writelane_b32 v255, s4, 10
	s_cselect_b32 s1, s0, 1
	s_cmp_lg_u32 s0, 1
	v_writelane_b32 v255, s5, 11
	s_cselect_b32 s1, s1, 6
	v_writelane_b32 v255, s2, 22
	s_and_b32 s19, s1, 1
	s_ashr_i32 s1, s1, 1
	v_writelane_b32 v255, s3, 23
	s_lshl_b32 s36, s0, 4
	s_lshl_b32 s2, s19, 5
	s_cmp_lt_i32 s0, 4
	s_cselect_b64 s[4:5], -1, 0
	s_movk_i32 s22, 0x1800
	v_writelane_b32 v255, s4, 20
	s_cmp_gt_i32 s0, 3
	v_mad_u32_u24 v4, v5, s22, v1
	v_writelane_b32 v255, s5, 21
	s_cselect_b64 s[4:5], -1, 0
	v_bfe_u32 v10, v2, 4, 2
	v_lshl_add_u32 v1, s0, 3, v4
	v_writelane_b32 v255, s4, 24
	s_lshl_b32 s3, s0, 9
	s_lshl_b32 s0, s0, 5
	v_readlane_b32 s18, v254, 51
	v_lshlrev_b32_e32 v15, 3, v10
	v_writelane_b32 v255, s5, 25
	s_add_i32 s3, s3, 0
	s_add_i32 s4, s18, s0
	s_add_i32 s3, s3, 0x16800
	v_add_u32_e32 v19, s4, v15
	s_add_i32 s20, s36, 0
	s_add_i32 s4, s2, 0
	s_lshl_b32 s14, s19, 1
	v_and_b32_e32 v11, 15, v2
	v_mul_u32_u24_e32 v12, 0x1800, v5
	s_cmp_le_i32 s14, s1
	v_add3_u32 v108, v4, v12, s36
	v_lshl_or_b32 v4, s1, 4, v11
	v_add_u32_e32 v20, s4, v15
	s_movk_i32 s4, 0x90
	s_cselect_b64 s[88:89], -1, 0
	s_cmp_eq_u32 s14, s1
	v_mul_lo_u32 v32, v4, s4
	s_cselect_b64 s[4:5], -1, 0
	s_lshl_b32 s68, s19, 6
	s_or_b32 s16, s14, 1
	s_cmp_ge_i32 s14, s1
	s_movk_i32 s24, 0x110
	s_cselect_b64 s[84:85], -1, 0
	s_cmp_eq_u32 s16, s1
	v_lshlrev_b32_e32 v13, 3, v2
	v_mad_u32_u24 v110, v5, s24, 0
	v_ashrrev_i32_e32 v24, 4, v2
	v_add_u32_e32 v26, 0x200, v2
	v_and_b32_e32 v111, 48, v2
	s_cselect_b64 s[14:15], -1, 0
	s_lshl_b32 s69, s16, 5
	v_mov_b32_e32 v36, s18
	s_movk_i32 s18, 0x60
	v_readlane_b32 s25, v254, 52
	v_and_b32_e32 v14, 0x78, v13
	v_lshlrev_b32_e32 v109, s100, v5
	v_lshlrev_b32_e32 v18, 2, v5
	v_lshl_add_u32 v23, v5, 4, v110
	v_ashrrev_i32_e32 v26, 4, v26
	v_mul_u32_u24_e32 v29, 0x60, v5
	v_lshl_or_b32 v33, s19, 7, v111
	s_cmp_eq_u32 s19, 0
	v_writelane_b32 v255, s19, 18
	v_lshl_or_b32 v35, s19, 4, v11
	v_mul_lo_u32 v37, v4, s18
	v_cmp_gt_u32_e64 s[18:19], 16, v5
	v_mov_b32_e32 v5, s25
	v_mul_lo_u32 v114, v24, s22
	v_lshlrev_b32_e32 v10, 2, v10
	v_mad_u32_u24 v36, v35, s24, v36
	v_mad_u32_u24 v35, v35, s24, v5
	v_mul_lo_u32 v115, v26, s22
	v_or_b32_e32 v5, v114, v14
	v_bfe_u32 v17, v2, 2, 2
	v_and_b32_e32 v13, 24, v13
	v_cmp_gt_u32_e64 s[6:7], v10, v11
	v_cmp_lt_u32_e64 s[8:9], v10, v11
	v_or_b32_e32 v34, 2, v10
	v_or_b32_e32 v10, 3, v10
	v_add_u32_e32 v118, 0x1400, v5
	v_or_b32_e32 v5, v115, v14
	s_mul_i32 s1, s1, 0x30000
	s_movk_i32 s23, 0x3000
	v_or_b32_e32 v17, v15, v17
	v_add_u32_e32 v13, 0, v13
	v_lshlrev_b32_e32 v22, 4, v2
	v_cmp_gt_u32_e64 s[10:11], v34, v11
	v_cmp_gt_u32_e64 s[12:13], v10, v11
	v_lshl_or_b32 v10, s16, 4, v11
	v_lshl_or_b32 v34, s16, 6, v111
	s_movk_i32 s16, 0x120
	v_add_u32_e32 v120, 0x1400, v5
	v_mov_b32_e32 v5, s1
	v_and_b32_e32 v22, 0xf0, v22
	v_mul_u32_u24_e32 v28, 0x60, v17
	v_mul_lo_u32 v30, v4, s24
	v_add_u32_e32 v112, s91, v32
	v_or_b32_e32 v32, s2, v11
	s_movk_i32 s16, 0x110
	v_mad_u32_u24 v194, v17, s16, v13
	s_movk_i32 s16, 0x120
	v_mad_u32_u24 v17, v17, s16, v13
	s_cselect_b64 s[16:17], -1, 0
	s_add_i32 s21, s25, s0
	v_mad_u32_u24 v5, v11, s23, v5
	v_mul_lo_u32 v16, v4, s23
	v_mul_u32_u24_e32 v21, 0x110, v11
	v_add_u32_e32 v22, 0, v22
	v_mul_lo_u32 v25, v24, s24
	v_mul_lo_u32 v27, v26, s24
	v_add_u32_e32 v30, 0, v30
	v_lshlrev_b32_e32 v2, 2, v4
	v_add_u32_e32 v31, 0, v111
	v_mul_u32_u24_e32 v32, 0x110, v32
	v_mul_u32_u24_e32 v10, 0x110, v10
	v_add_u32_e32 v38, s21, v15
	s_add_i32 s21, s36, 0x2080
	v_or3_b32 v121, v5, s2, v15
	v_ashrrev_i32_e32 v5, 31, v4
	v_readlane_b32 s80, v253, 61
	s_mov_b32 s26, 0x9300000
	v_add_u32_e32 v113, v112, v15
	v_or3_b32 v116, v16, v15, s2
	v_or_b32_e32 v117, 0x1400, v14
	v_lshl_add_u32 v119, v12, 1, s21
	v_lshlrev_b64 v[74:75], 2, v[4:5]
	v_add_u32_e32 v122, v19, v21
	v_add_u32_e32 v123, v36, v111
	v_add_u32_e32 v124, v38, v21
	v_add_u32_e32 v125, v35, v111
	v_add_u32_e32 v126, s3, v18
	v_add_u32_e32 v127, v22, v25
	v_add_u32_e32 v128, s36, v23
	v_add_u32_e32 v129, v22, v27
	v_add_u32_e32 v130, s20, v29
	v_add_u32_e32 v131, v30, v111
	v_add_u32_e32 v132, s3, v2
	v_add_u32_e32 v133, v31, v32
	v_add_u32_e32 v134, s3, v33
	v_add_u32_e32 v135, v31, v10
	v_add_u32_e32 v136, s3, v34
	v_add_u32_e32 v137, s0, v17
	v_add_u32_e32 v138, v13, v28
	v_add_u32_e32 v194, s0, v194
	v_add_u32_e32 v83, 32, v138
	v_cndmask_b32_e64 v83, v83, v138, s[16:17]
	v_add_u32_e32 v139, v20, v37
	v_lshrrev_b32_e32 v189, 4, v0
	v_and_b32_e32 v188, 15, v0
	s_movk_i32 s2, 0x120
	v_lshlrev_b32_e32 v188, 4, v188
	v_mad_u32_u24 v188, v189, s2, v188
	v_lshlrev_b32_e32 v189, 2, v189
	v_add_u32_e32 v190, 0x80, v189
	v_and_b32_e32 v76, 63, v0
	v_lshrrev_b32_e32 v77, 2, v76
	v_add_u32_e32 v77, s36, v77
	v_lshlrev_b32_e32 v195, 2, v77
	v_and_b32_e32 v76, 3, v76
	v_lshlrev_b32_e32 v76, 4, v76
	s_movk_i32 s2, 0x3000
	v_mad_u32_u24 v108, v77, s2, v76
	v_add_u32_e32 v108, 0x1000, v108
	s_movk_i32 s2, 0x60
	v_mad_u32_u24 v130, v77, s2, v76
	s_mov_b32 s72, s92
	s_mov_b32 s73, s92
	v_readlane_b32 s81, v253, 62
	s_branch .LBB0_710

; #define LAS __attribute__((address_space(3)))
; __device__ __forceinline__ unsigned pk2(float lo, float hi) { unsigned r; asm volatile("v_cvt_pk_bf16_f32 %0, %1, %2" : "=v"(r) : "v"(lo), "v"(hi)); return r; }
; template <int CTRL> __device__ __forceinline__ float dppz(float x) { return __builtin_bit_cast(float, __builtin_amdgcn_update_dpp(0, __builtin_bit_cast(int, x), CTRL, 0xf, 0xf, true)); }
; template <bool DRY>
; __device__ __forceinline__ void ssd_chunk(SsdRegs& R, f32x4 (&st)[2], LAS unsigned char* L, bf16_t* BIG, const float* DT, float* SSQY, const SsdItem& I, int c, int tid, int lane, int wave, int li, int pi, int c16, int q4) {
;     ...
;     const float dtl = R.rdt;
;     float acs = dtl * I.Ah;
;     acs += dppz<0x111>(acs); acs += dppz<0x112>(acs); acs += dppz<0x114>(acs); acs += dppz<0x118>(acs);
;     acs += __builtin_bit_cast(float, __builtin_amdgcn_update_dpp(0, __builtin_bit_cast(int, acs), 0x142, 0xa, 0xf, false));
;     acs += __builtin_bit_cast(float, __builtin_amdgcn_update_dpp(0, __builtin_bit_cast(int, acs), 0x143, 0xc, 0xf, false));
;     const float tot = __builtin_bit_cast(float, __builtin_amdgcn_readlane(__builtin_bit_cast(int, acs), 63));
;     const float wl = dtl * __expf(tot - acs), etot = __expf(tot);
;     LAS unsigned char* SCW = L + SCT + wave * 512;
;     *(LAS float*)(SCW + lane * 4) = acs; *(LAS float*)(SCW + 256 + lane * 4) = dtl;
; #pragma unroll
;     for (int pt = 0; pt < 2; ++pt) { u32x2 w; w.x = pk2(st[pt][0], st[pt][1]); w.y = pk2(st[pt][2], st[pt][3]); *(LAS u32x2*)(L + SB + (16 * pt + c16) * PC + (16 * wave + 4 * q4) * 2) = w; }
; #pragma unroll
;     for (int i = 0; i < 2; ++i) {
;         const int id = tid + 512 * i; *(LAS u32x4*)(L + CS + (id >> 4) * PC + (id & 15) * 16) = (u32x4){R.rc[i].x, R.rc[i].y, R.rc[i].z, R.rc[i].w};
;         const int n8 = wave + 8 * i; *(LAS u32x4*)(L + BS + lane * PC + n8 * 16) = (u32x4){R.rb[i].x, R.rb[i].y, R.rb[i].z, R.rb[i].w};
;         float f[8]; unpack8(R.rb[i], f);
;         u32x4 bwv; bwv.x = pk2(f[0] * wl, f[1] * wl); bwv.y = pk2(f[2] * wl, f[3] * wl); bwv.z = pk2(f[4] * wl, f[5] * wl); bwv.w = pk2(f[6] * wl, f[7] * wl);
;         *(LAS u32x4*)(L + BW + lane * PB + n8 * 16) = bwv;
;     }
;     if (wave < 4) *(LAS u32x4*)(L + XI + lane * PX + wave * 16) = (u32x4){R.rx.x, R.rx.y, R.rx.z, R.rx.w};
;     const u32x2 zc = R.rz;
;     __syncthreads();
.LBB0_720:
	s_waitcnt vmcnt(6)
	v_mul_f32_e64 v65, v140, -v141
	v_mov_b32_e32 v66, 0
	v_add_u32_e32 v142, s36, v110
	v_mov_b32_dpp v65, v65 row_shr:1 row_mask:0xf bank_mask:0xf bound_ctrl:1
	v_fma_f32 v65, v140, -v141, v65
	s_and_b64 vcc, exec, s[20:21]
	s_nop 0
	v_add_f32_dpp v65, v65, v65 row_shr:2 row_mask:0xf bank_mask:0xf bound_ctrl:1
	s_nop 1
	v_add_f32_dpp v65, v65, v65 row_shr:4 row_mask:0xf bank_mask:0xf bound_ctrl:1
	s_nop 1
	v_add_f32_dpp v65, v65, v65 row_shr:8 row_mask:0xf bank_mask:0xf bound_ctrl:1
	s_nop 1
	v_mov_b32_dpp v66, v65 row_bcast:15 row_mask:0xa bank_mask:0xf
	v_add_f32_e32 v65, v65, v66
	v_mov_b32_e32 v66, 0
	s_nop 1
	v_mov_b32_dpp v66, v65 row_bcast:31 row_mask:0xc bank_mask:0xf
	v_add_f32_e32 v65, v65, v66
	ds_write2st64_b32 v126, v65, v140 offset1:1
	v_readlane_b32 s3, v65, 63
	v_cvt_pk_bf16_f32 v58, v50, v58
	v_cvt_pk_bf16_f32 v59, v59, v61
	ds_write_b64 v122, v[58:59]
	v_cvt_pk_bf16_f32 v58, v60, v62
	v_cvt_pk_bf16_f32 v59, v63, v64
	s_nop 0
	v_sub_f32_e32 v66, s3, v65
	v_exp_f32_e32 v66, v66
	ds_write_b64 v122, v[58:59] offset:4352
	ds_write_b128 v127, v[14:17]
	ds_write_b128 v127, v[10:13] offset:17408
	v_mul_f32_e32 v62, v140, v66
	ds_write_b128 v129, v[22:25]
	ds_write_b128 v129, v[18:21] offset:17408
	s_cbranch_vccnz .LBB0_722
	ds_bpermute_b32 v82, v195, v62
	ds_write_b128 v130, v[26:29] offset:53248
	v_lshlrev_b32_e32 v58, 16, v26
	v_and_b32_e32 v59, 0xffff0000, v26
	v_lshlrev_b32_e32 v60, 16, v27
	v_and_b32_e32 v61, 0xffff0000, v27
	v_lshlrev_b32_e32 v64, 16, v28
	v_and_b32_e32 v65, 0xffff0000, v28
	v_lshlrev_b32_e32 v66, 16, v29
	v_and_b32_e32 v67, 0xffff0000, v29
	s_waitcnt lgkmcnt(1)
	v_pk_mul_f32 v[58:59], v[58:59], v[82:83] op_sel_hi:[1,0]
	v_pk_mul_f32 v[60:61], v[60:61], v[82:83] op_sel_hi:[1,0]
	v_pk_mul_f32 v[64:65], v[64:65], v[82:83] op_sel_hi:[1,0]
	v_pk_mul_f32 v[66:67], v[66:67], v[82:83] op_sel_hi:[1,0]
	v_cvt_pk_bf16_f32 v58, v58, v59
	v_cvt_pk_bf16_f32 v59, v60, v61
	v_cvt_pk_bf16_f32 v60, v64, v65
	v_cvt_pk_bf16_f32 v61, v66, v67
	ds_write_b128 v130, v[58:61] offset:34816

; #define LAS __attribute__((address_space(3)))
; template <bool DRY>
; __device__ __forceinline__ void ssd_chunk(SsdRegs& R, f32x4 (&st)[2], LAS unsigned char* L, bf16_t* BIG, const float* DT, float* SSQY, const SsdItem& I, int c, int tid, int lane, int wave, int li, int pi, int c16, int q4) {
;     ...
;     const float dtl = R.rdt;
;     float acs = dtl * I.Ah;
;     ...
;     f32x4 stn[2];
;     bf16x8 xfr[2][2], bwf[2];
; #pragma unroll
;     for (int kk = 0; kk < 2; ++kk) { bwf[kk] = SSD_TR(BW, PB, trB, wave, kk); xfr[0][kk] = SSD_TR(XI, PX, trX, 0, kk); xfr[1][kk] = SSD_TR(XI, PX, trX, 1, kk); }
; #pragma unroll
;     for (int pt = 0; pt < 2; ++pt) {
;         f32x4 d = st[pt] * etot;
; #pragma unroll
;         for (int kk = 0; kk < 2; ++kk) d = __builtin_amdgcn_mfma_f32_16x16x32_bf16(bwf[kk], xfr[pt][kk], d, 0, 0, 0);
;         stn[pt] = d;
;     }
;     const bf16x8 xy0 = pi ? xfr[1][0] : xfr[0][0], xy1 = pi ? xfr[1][1] : xfr[0][1];
;     st[0] = stn[0]; st[1] = stn[1];
;     __syncthreads();
;     {
;         f32x4 d1 = (f32x4){0.f, 0.f, 0.f, 0.f}, d2 = (f32x4){0.f, 0.f, 0.f, 0.f};
; #pragma unroll
;         for (int kk = 0; kk < 2; ++kk) d1 = __builtin_amdgcn_mfma_f32_16x16x32_bf16(kk ? xy1 : xy0, SSD_FRAG(GG, PT, 16 * li, kk), d1, 0, 0, 0);
; #pragma unroll
;         for (int kk = 0; kk < 4; ++kk) d2 = __builtin_amdgcn_mfma_f32_16x16x32_bf16(SSD_FRAG(SB, PC, 16 * pi, kk), cfr[kk], d2, 0, 0, 0);
;         const int l = 16 * li + c16; const float ea_l = __expf(*(const LAS float*)(SCW + l * 4));
;         const float zf[4] = {bf_lo(zc.x), bf_hi(zc.x), bf_lo(zc.y), bf_hi(zc.y)};
;         float yg[4], sq = 0.f;
;         const u32x2 xr = *(const LAS u32x2*)(L + XI + l * PX + (16 * pi + 4 * q4) * 2);
;         const float xs[4] = {bf_lo(xr.x), bf_hi(xr.x), bf_lo(xr.y), bf_hi(xr.y)};
; #pragma unroll
;         for (int e = 0; e < 4; ++e) { const float xv = xs[e];
;             const float y = d1[e] + ea_l * d2[e] + I.Dh * xv; yg[e] = y * silu_f(zf[e]); sq += yg[e] * yg[e]; }
;         u32x2 w; w.x = pk2(yg[0], yg[1]); w.y = pk2(yg[2], yg[3]);
;         if (!DRY) *(u32x2*)((char*)BIG + row0 * (BIGW * 2) + I.offZ) = w;
;         sq += __shfl_xor(sq, 16); sq += __shfl_xor(sq, 32);
;         if (DRY) { if (sq == 12345.678f) SSQY[0] = 1.f; } else if (q4 == 0) SSQY[(size_t)(I.h * 4 + I.ph * 2 + pi) * M_ + row0 + l] = sq;
;     }
.LBB0_733:
	v_add_u32_e32 v145, s69, v113
	s_waitcnt lgkmcnt(1)
	ds_write_b64 v145, v[106:107]
	ds_read_b64_tr_b16 v[146:147], v194 offset:17408
	ds_read_b64_tr_b16 v[148:149], v194 offset:18496
	v_exp_f32_e32 v76, s3
	ds_read_b64_tr_b16 v[152:153], v138 offset:35200
	ds_read_b64_tr_b16 v[150:151], v138 offset:34816
	ds_read_b64_tr_b16 v[154:155], v194 offset:26112
	ds_read_b64_tr_b16 v[156:157], v194 offset:27200
	ds_read_b64_tr_b16 v[158:159], v138 offset:37888
	ds_read_b64_tr_b16 v[160:161], v138 offset:38272
	ds_read_b64_tr_b16 v[162:163], v138 offset:34848
	ds_read_b64_tr_b16 v[164:165], v138 offset:35232
	ds_read_b64_tr_b16 v[166:167], v138 offset:37920
	ds_read_b64_tr_b16 v[168:169], v138 offset:38304
	v_pk_mul_f32 v[52:53], v[52:53], v[76:77] op_sel_hi:[1,0]
	v_pk_mul_f32 v[50:51], v[50:51], v[76:77] op_sel_hi:[1,0]
	v_pk_mul_f32 v[56:57], v[56:57], v[76:77] op_sel_hi:[1,0]
	v_pk_mul_f32 v[54:55], v[54:55], v[76:77] op_sel_hi:[1,0]
	s_waitcnt lgkmcnt(8)
	v_mfma_f32_16x16x32_bf16 v[50:53], v[146:149], v[150:153], v[50:53]
	ds_read_b64_tr_b16 v[196:197], v83 offset:53248
	ds_read_b64_tr_b16 v[198:199], v83 offset:53632
	ds_read_b64_tr_b16 v[200:201], v83 offset:56320
	ds_read_b64_tr_b16 v[202:203], v83 offset:56704
	v_add_u32_e32 v143, v112, v111
	s_waitcnt lgkmcnt(0)
	s_barrier
	v_mfma_f32_16x16x32_bf16 v[54:57], v[146:149], v[162:165], v[54:57]
	v_mfma_f32_16x16x32_bf16 v[50:53], v[154:157], v[158:161], v[50:53]
	v_cmp_lt_i32_e32 vcc, v213, v208
	v_cmp_lt_i32_e64 s[0:1], v214, v208
	v_mfma_f32_16x16x32_bf16 v[54:57], v[154:157], v[166:169], v[54:57]
	ds_read_b128 v[150:153], v143
	ds_read_b128 v[154:157], v123
	ds_read_b32 v76, v132
	s_waitcnt lgkmcnt(2)
	v_mfma_f32_16x16x32_bf16 v[146:149], v[196:199], v[150:153], 0
	ds_read_b128 v[150:153], v123 offset:64
	s_waitcnt lgkmcnt(2)
	v_mfma_f32_16x16x32_bf16 v[70:73], v[154:157], v[70:73], 0
	ds_read_b128 v[154:157], v123 offset:128
	s_waitcnt lgkmcnt(1)
	v_mfma_f32_16x16x32_bf16 v[66:69], v[150:153], v[66:69], v[70:73]
	s_nop 4
	ds_read_b128 v[70:73], v123 offset:192
	s_waitcnt lgkmcnt(1)
	v_mfma_f32_16x16x32_bf16 v[62:65], v[154:157], v[62:65], v[66:69]
	s_nop 2
	ds_read_b128 v[66:69], v143 offset:64
	s_waitcnt lgkmcnt(1)
	v_mfma_f32_16x16x32_bf16 v[58:61], v[70:73], v[58:61], v[62:65]
	v_lshlrev_b32_e32 v70, 16, v96
	s_nop 1
	v_exp_f32_e32 v72, v76
	v_mul_f32_e32 v62, 0xbfb8aa3b, v70
	v_exp_f32_e32 v71, v62
	s_waitcnt lgkmcnt(0)
	v_mfma_f32_16x16x32_bf16 v[62:65], v[200:203], v[66:69], v[146:149]
	ds_read_b64 v[66:67], v139 offset:53248
	s_nop 6
	v_fma_f32 v62, v58, v72, v62
	v_add_f32_e32 v58, 1.0, v71
	v_rcp_f32_e32 v76, v58
	v_and_b32_e32 v58, 0xffff0000, v96
	v_mul_f32_e32 v68, 0xbfb8aa3b, v58
	v_exp_f32_e32 v73, v68
	s_waitcnt lgkmcnt(0)
	v_lshlrev_b32_e32 v71, 16, v66
	v_pk_mul_f32 v[68:69], v[76:77], v[70:71]
	v_fma_f32 v63, v59, v72, v63
	v_add_f32_e32 v62, v62, v69
	v_add_f32_e32 v69, 1.0, v73
	v_rcp_f32_e32 v76, v69
	v_and_b32_e32 v59, 0xffff0000, v66
	v_mul_f32_e32 v62, v68, v62
	v_fma_f32 v64, v60, v72, v64
	v_pk_mul_f32 v[58:59], v[76:77], v[58:59]
	v_fmac_f32_e32 v65, v61, v72
	v_add_f32_e32 v59, v63, v59
	v_mul_f32_e32 v63, v58, v59
	v_lshlrev_b32_e32 v58, 16, v97
	v_mul_f32_e32 v59, 0xbfb8aa3b, v58
	v_exp_f32_e32 v68, v59
	v_lshlrev_b32_e32 v59, 16, v67
	v_and_b32_e32 v61, 0xffff0000, v67
	v_mul_f32_e32 v66, v63, v63
	v_add_f32_e32 v60, 1.0, v68
	v_rcp_f32_e32 v76, v60
	v_and_b32_e32 v60, 0xffff0000, v97
	v_mul_f32_e32 v68, 0xbfb8aa3b, v60
	v_exp_f32_e32 v68, v68
	v_pk_mul_f32 v[58:59], v[76:77], v[58:59]
	v_fmac_f32_e32 v66, v62, v62
	v_add_f32_e32 v59, v64, v59
	v_mul_f32_e32 v64, v58, v59
	v_add_f32_e32 v58, 1.0, v68
	v_rcp_f32_e32 v76, v58
	v_fmac_f32_e32 v66, v64, v64
	v_pk_mul_f32 v[58:59], v[76:77], v[60:61]
	s_nop 0
	v_add_f32_e32 v59, v65, v59
	v_mul_f32_e32 v58, v58, v59
	v_cndmask_b32_e32 v59, v207, v213, vcc
	v_fmac_f32_e32 v66, v58, v58
	v_lshlrev_b32_e32 v146, 2, v59
	ds_bpermute_b32 v59, v146, v66
	v_cvt_pk_bf16_f32 v60, v62, v63
	v_cvt_pk_bf16_f32 v61, v64, v58
	s_waitcnt lgkmcnt(0)
	v_add_f32_e32 v58, v66, v59
	v_cndmask_b32_e64 v59, v207, v214, s[0:1]
	v_lshlrev_b32_e32 v147, 2, v59
	ds_bpermute_b32 v59, v147, v58
	global_store_dwordx2 v[78:79], v[60:61], off
	s_mov_b64 s[0:1], 0xc0000
	v_lshl_add_u64 v[78:79], v[78:79], 0, s[0:1]
	s_and_saveexec_b64 s[0:1], s[18:19]
	s_cbranch_execz .LBB0_735
	s_waitcnt lgkmcnt(0)
	v_add_f32_e32 v60, v58, v59
	global_store_dword v[90:91], v60, off
.LBB0_735:
	s_or_b64 exec, exec, s[0:1]
	s_waitcnt vmcnt(1)
	v_mul_f32_e64 v58, v2, -v141
	s_waitcnt lgkmcnt(0)
	v_mov_b32_e32 v59, 0
	s_nop 0
	v_mov_b32_dpp v58, v58 row_shr:1 row_mask:0xf bank_mask:0xf bound_ctrl:1
	v_fma_f32 v58, v2, -v141, v58
	s_nop 0
	s_nop 0
	v_add_f32_dpp v58, v58, v58 row_shr:2 row_mask:0xf bank_mask:0xf bound_ctrl:1
	s_nop 0
	s_nop 0
	v_add_f32_dpp v58, v58, v58 row_shr:4 row_mask:0xf bank_mask:0xf bound_ctrl:1
	s_and_b64 vcc, exec, s[20:21]
	s_nop 0
	v_add_f32_dpp v58, v58, v58 row_shr:8 row_mask:0xf bank_mask:0xf bound_ctrl:1
	s_nop 1
	v_mov_b32_dpp v59, v58 row_bcast:15 row_mask:0xa bank_mask:0xf
	v_add_f32_e32 v58, v58, v59
	v_mov_b32_e32 v59, 0
	s_nop 1
	v_mov_b32_dpp v59, v58 row_bcast:31 row_mask:0xc bank_mask:0xf
	v_add_f32_e32 v58, v58, v59
	ds_write2st64_b32 v126, v58, v2 offset1:1
	v_readlane_b32 s3, v58, 63
	s_nop 1
	v_sub_f32_e32 v59, s3, v58
	v_exp_f32_e32 v60, v59
	v_cvt_pk_bf16_f32 v58, v50, v51
	v_cvt_pk_bf16_f32 v59, v52, v53
	ds_write_b64 v124, v[58:59]
	v_cvt_pk_bf16_f32 v58, v54, v55
	v_cvt_pk_bf16_f32 v59, v56, v57
	ds_write_b64 v124, v[58:59] offset:4352
	ds_write_b128 v127, v[34:37]
	ds_write_b128 v127, v[30:33] offset:17408
	v_mul_f32_e32 v62, v2, v60
	ds_write_b128 v129, v[46:49]
	ds_write_b128 v129, v[42:45] offset:17408
	s_cbranch_vccnz .LBB0_737
	ds_bpermute_b32 v82, v195, v62
	ds_write_b128 v130, v[38:41] offset:59392
	v_lshlrev_b32_e32 v58, 16, v38
	v_and_b32_e32 v59, 0xffff0000, v38
	v_lshlrev_b32_e32 v60, 16, v39
	v_and_b32_e32 v61, 0xffff0000, v39
	v_lshlrev_b32_e32 v64, 16, v40
	v_and_b32_e32 v65, 0xffff0000, v40
	v_lshlrev_b32_e32 v66, 16, v41
	v_and_b32_e32 v67, 0xffff0000, v41
	s_waitcnt lgkmcnt(1)
	v_pk_mul_f32 v[58:59], v[58:59], v[82:83] op_sel_hi:[1,0]
	v_pk_mul_f32 v[60:61], v[60:61], v[82:83] op_sel_hi:[1,0]
	v_pk_mul_f32 v[64:65], v[64:65], v[82:83] op_sel_hi:[1,0]
	v_pk_mul_f32 v[66:67], v[66:67], v[82:83] op_sel_hi:[1,0]
	v_cvt_pk_bf16_f32 v58, v58, v59
	v_cvt_pk_bf16_f32 v59, v60, v61
	v_cvt_pk_bf16_f32 v60, v64, v65
	v_cvt_pk_bf16_f32 v61, v66, v67
	ds_write_b128 v130, v[58:61] offset:34816

; #define LAS __attribute__((address_space(3)))
; __device__ __forceinline__ float bf_lo(unsigned w) { return __uint_as_float(w << 16); }
; template <bool DRY>
; __device__ __forceinline__ void ssd_chunk(SsdRegs& R, f32x4 (&st)[2], LAS unsigned char* L, bf16_t* BIG, const float* DT, float* SSQY, const SsdItem& I, int c, int tid, int lane, int wave, int li, int pi, int c16, int q4) {
;     ...
;     f32x4 stn[2];
;     bf16x8 xfr[2][2], bwf[2];
; #pragma unroll
;     for (int kk = 0; kk < 2; ++kk) { bwf[kk] = SSD_TR(BW, PB, trB, wave, kk); xfr[0][kk] = SSD_TR(XI, PX, trX, 0, kk); xfr[1][kk] = SSD_TR(XI, PX, trX, 1, kk); }
; #pragma unroll
;     for (int pt = 0; pt < 2; ++pt) {
;         f32x4 d = st[pt] * etot;
; #pragma unroll
;         for (int kk = 0; kk < 2; ++kk) d = __builtin_amdgcn_mfma_f32_16x16x32_bf16(bwf[kk], xfr[pt][kk], d, 0, 0, 0);
;         stn[pt] = d;
;     }
;     const bf16x8 xy0 = pi ? xfr[1][0] : xfr[0][0], xy1 = pi ? xfr[1][1] : xfr[0][1];
;     st[0] = stn[0]; st[1] = stn[1];
;     __syncthreads();
;     {
;         f32x4 d1 = (f32x4){0.f, 0.f, 0.f, 0.f}, d2 = (f32x4){0.f, 0.f, 0.f, 0.f};
; #pragma unroll
;         for (int kk = 0; kk < 2; ++kk) d1 = __builtin_amdgcn_mfma_f32_16x16x32_bf16(kk ? xy1 : xy0, SSD_FRAG(GG, PT, 16 * li, kk), d1, 0, 0, 0);
; #pragma unroll
;         for (int kk = 0; kk < 4; ++kk) d2 = __builtin_amdgcn_mfma_f32_16x16x32_bf16(SSD_FRAG(SB, PC, 16 * pi, kk), cfr[kk], d2, 0, 0, 0);
;         const int l = 16 * li + c16; const float ea_l = __expf(*(const LAS float*)(SCW + l * 4));
;         const float zf[4] = {bf_lo(zc.x), bf_hi(zc.x), bf_lo(zc.y), bf_hi(zc.y)};
;         float yg[4], sq = 0.f;
;         const u32x2 xr = *(const LAS u32x2*)(L + XI + l * PX + (16 * pi + 4 * q4) * 2);
;         const float xs[4] = {bf_lo(xr.x), bf_hi(xr.x), bf_lo(xr.y), bf_hi(xr.y)};
; #pragma unroll
;         for (int e = 0; e < 4; ++e) { const float xv = xs[e];
;             const float y = d1[e] + ea_l * d2[e] + I.Dh * xv; yg[e] = y * silu_f(zf[e]); sq += yg[e] * yg[e]; }
;         u32x2 w; w.x = pk2(yg[0], yg[1]); w.y = pk2(yg[2], yg[3]);
;         if (!DRY) *(u32x2*)((char*)BIG + row0 * (BIGW * 2) + I.offZ) = w;
;         sq += __shfl_xor(sq, 16); sq += __shfl_xor(sq, 32);
;         if (DRY) { if (sq == 12345.678f) SSQY[0] = 1.f; } else if (q4 == 0) SSQY[(size_t)(I.h * 4 + I.ph * 2 + pi) * M_ + row0 + l] = sq;
;     }
.LBB0_746:
	s_waitcnt lgkmcnt(1)
	v_exp_f32_e32 v76, s3
	ds_write_b64 v145, v[100:101]
	ds_read_b64_tr_b16 v[100:101], v194 offset:17408
	ds_read_b64_tr_b16 v[102:103], v194 offset:18496
	ds_read_b64_tr_b16 v[150:151], v138 offset:35200
	ds_read_b64_tr_b16 v[148:149], v138 offset:34816
	ds_read_b64_tr_b16 v[152:153], v194 offset:26112
	ds_read_b64_tr_b16 v[154:155], v194 offset:27200
	ds_read_b64_tr_b16 v[156:157], v138 offset:37888
	ds_read_b64_tr_b16 v[158:159], v138 offset:38272
	ds_read_b64_tr_b16 v[162:163], v138 offset:35232
	ds_read_b64_tr_b16 v[160:161], v138 offset:34848
	ds_read_b64_tr_b16 v[166:167], v138 offset:38304
	v_pk_mul_f32 v[52:53], v[52:53], v[76:77] op_sel_hi:[1,0]
	v_pk_mul_f32 v[50:51], v[50:51], v[76:77] op_sel_hi:[1,0]
	ds_read_b64_tr_b16 v[164:165], v138 offset:37920
	v_pk_mul_f32 v[56:57], v[56:57], v[76:77] op_sel_hi:[1,0]
	v_pk_mul_f32 v[54:55], v[54:55], v[76:77] op_sel_hi:[1,0]
	s_waitcnt lgkmcnt(8)
	v_mfma_f32_16x16x32_bf16 v[50:53], v[100:103], v[148:151], v[50:53]
	ds_read_b64_tr_b16 v[196:197], v83 offset:59392
	ds_read_b64_tr_b16 v[198:199], v83 offset:59776
	ds_read_b64_tr_b16 v[200:201], v83 offset:62464
	ds_read_b64_tr_b16 v[202:203], v83 offset:62848
	s_waitcnt lgkmcnt(0)
	s_barrier
	v_mfma_f32_16x16x32_bf16 v[54:57], v[100:103], v[160:163], v[54:57]
	v_mfma_f32_16x16x32_bf16 v[50:53], v[152:155], v[156:159], v[50:53]
	ds_read_b128 v[148:151], v143
	v_mfma_f32_16x16x32_bf16 v[54:57], v[152:155], v[164:167], v[54:57]
	ds_read_b128 v[152:155], v125
	s_waitcnt lgkmcnt(1)
	v_mfma_f32_16x16x32_bf16 v[100:103], v[196:199], v[148:151], 0
	ds_read_b128 v[148:151], v125 offset:64
	s_waitcnt lgkmcnt(1)
	v_mfma_f32_16x16x32_bf16 v[70:73], v[152:155], v[70:73], 0
	ds_read_b128 v[152:155], v125 offset:128
	s_waitcnt lgkmcnt(1)
	v_mfma_f32_16x16x32_bf16 v[66:69], v[148:151], v[66:69], v[70:73]
	s_nop 4
	ds_read_b128 v[70:73], v125 offset:192
	ds_read_b32 v76, v132
	s_waitcnt lgkmcnt(2)
	v_mfma_f32_16x16x32_bf16 v[62:65], v[152:155], v[62:65], v[66:69]
	s_nop 2
	v_lshlrev_b32_e32 v68, 16, v92
	s_waitcnt lgkmcnt(1)
	v_mfma_f32_16x16x32_bf16 v[58:61], v[70:73], v[58:61], v[62:65]
	v_mul_f32_e32 v69, 0xbfb8aa3b, v68
	v_exp_f32_e32 v69, v69
	s_waitcnt lgkmcnt(0)
	v_exp_f32_e32 v70, v76
	ds_read_b128 v[62:65], v143 offset:64
	ds_read_b64 v[66:67], v139 offset:59392
	s_waitcnt lgkmcnt(1)
	v_mfma_f32_16x16x32_bf16 v[62:65], v[200:203], v[62:65], v[100:103]
	s_nop 7
	v_fma_f32 v62, v58, v70, v62
	v_add_f32_e32 v58, 1.0, v69
	v_rcp_f32_e32 v76, v58
	v_and_b32_e32 v58, 0xffff0000, v92
	v_mul_f32_e32 v69, 0xbfb8aa3b, v58
	v_exp_f32_e32 v71, v69
	s_waitcnt lgkmcnt(0)
	v_lshlrev_b32_e32 v69, 16, v66
	v_pk_mul_f32 v[68:69], v[76:77], v[68:69]
	v_fma_f32 v63, v59, v70, v63
	v_add_f32_e32 v62, v62, v69
	v_add_f32_e32 v69, 1.0, v71
	v_rcp_f32_e32 v76, v69
	v_and_b32_e32 v59, 0xffff0000, v66
	v_mul_f32_e32 v62, v68, v62
	v_fma_f32 v64, v60, v70, v64
	v_pk_mul_f32 v[58:59], v[76:77], v[58:59]
	v_fmac_f32_e32 v65, v61, v70
	v_add_f32_e32 v59, v63, v59
	v_mul_f32_e32 v63, v58, v59
	v_lshlrev_b32_e32 v58, 16, v93
	v_mul_f32_e32 v59, 0xbfb8aa3b, v58
	v_exp_f32_e32 v68, v59
	v_lshlrev_b32_e32 v59, 16, v67
	v_and_b32_e32 v61, 0xffff0000, v67
	v_mul_f32_e32 v66, v63, v63
	v_add_f32_e32 v60, 1.0, v68
	v_rcp_f32_e32 v76, v60
	v_and_b32_e32 v60, 0xffff0000, v93
	v_mul_f32_e32 v68, 0xbfb8aa3b, v60
	v_exp_f32_e32 v68, v68
	v_pk_mul_f32 v[58:59], v[76:77], v[58:59]
	v_fmac_f32_e32 v66, v62, v62
	v_add_f32_e32 v59, v64, v59
	v_mul_f32_e32 v64, v58, v59
	v_add_f32_e32 v58, 1.0, v68
	v_rcp_f32_e32 v76, v58
	v_fmac_f32_e32 v66, v64, v64
	v_pk_mul_f32 v[58:59], v[76:77], v[60:61]
	s_nop 0
	v_add_f32_e32 v59, v65, v59
	v_mul_f32_e32 v58, v58, v59
	v_fmac_f32_e32 v66, v58, v58
	ds_bpermute_b32 v59, v146, v66
	v_cvt_pk_bf16_f32 v60, v62, v63
	v_cvt_pk_bf16_f32 v61, v64, v58
	s_waitcnt lgkmcnt(0)
	v_add_f32_e32 v58, v66, v59
	ds_bpermute_b32 v59, v147, v58
	global_store_dwordx2 v[78:79], v[60:61], off
	s_mov_b64 s[0:1], 0xc0000
	v_lshl_add_u64 v[78:79], v[78:79], 0, s[0:1]
	s_and_saveexec_b64 s[0:1], s[18:19]
	s_cbranch_execz .LBB0_719
	s_waitcnt lgkmcnt(0)
	v_add_f32_e32 v60, v58, v59
	global_store_dword v[90:91], v60, off offset:256
	s_branch .LBB0_719
